# v222 + P5 (GLU GEMM): accumulator zeroing removed, peeled first K-loop iteration with MFMA C = inline 0 (same as P1/P7/P9/P10)
# baseline (speedup 1.0000x reference)
.LBB0_348:
	s_ashr_i32 s41, s40, 31
	v_cmp_lt_i64_e32 vcc, s[42:43], v[196:197]
	s_lshl_b64 s[42:43], s[40:41], 19
	s_add_u32 s42, s0, s42
	s_addc_u32 s43, s1, s43
	s_and_b64 s[44:45], vcc, exec
	s_cselect_b32 s41, s43, s53
	s_cselect_b32 s51, s42, s52
	s_ashr_i32 s39, s38, 31
	s_lshl_b64 s[44:45], s[38:39], 19
	s_add_u32 s44, s35, s44
	s_addc_u32 s45, s58, s45
	s_and_b64 s[56:57], vcc, exec
	s_cselect_b32 s39, s45, s55
	s_cselect_b32 s77, s44, s54
	s_add_u32 s52, s52, 0x40080
	s_addc_u32 s53, s53, 0
	s_add_u32 s78, s54, 0x100
	s_addc_u32 s79, s55, 0
	s_mov_b32 s80, -2
	s_waitcnt lgkmcnt(0)
	ds_read_b128 v[56:59], v217
	ds_read_b128 v[60:63], v217 offset:1024
	ds_read_b128 v[64:67], v217 offset:2048
	ds_read_b128 v[68:71], v217 offset:3072
	ds_read_b128 v[72:75], v218
	ds_read_b128 v[76:79], v218 offset:1024
	ds_read_b128 v[80:83], v218 offset:2048
	ds_read_b128 v[84:87], v218 offset:3072
	s_add_u32 s54, s52, 0xfffc0080
	s_addc_u32 s55, s53, -1
	s_cmp_eq_u32 s80, 12
	s_cselect_b32 s57, s41, s55
	s_cselect_b32 s56, s51, s54
	s_cselect_b32 s55, s39, s79
	s_cselect_b32 s54, s77, s78
	v_lshl_add_u64 v[208:209], s[52:53], 0, v[192:193]
	s_add_i32 m0, s64, 0xc000
	ds_read_b128 v[144:147], v219
	ds_read_b128 v[156:159], v219 offset:1024
	ds_read_b128 v[168:171], v219 offset:2048
	ds_read_b128 v[172:175], v219 offset:3072
	ds_read_b128 v[176:179], v219 offset:4096
	ds_read_b128 v[180:183], v219 offset:5120
	ds_read_b128 v[200:203], v219 offset:6144
	ds_read_b128 v[204:207], v219 offset:7168
	global_load_lds_dwordx4 v[208:209], off
	v_lshl_add_u64 v[208:209], s[52:53], 0, v[194:195]
	s_add_i32 m0, s64, 0xe000
	s_nop 0
	global_load_lds_dwordx4 v[208:209], off
	s_waitcnt vmcnt(8)
	s_waitcnt lgkmcnt(0)
	s_barrier
	s_setprio 1
	s_waitcnt lgkmcnt(0)
	v_mfma_f32_16x16x32_bf16 v[164:167], v[56:59], v[144:147], 0
	v_mfma_f32_16x16x32_bf16 v[160:163], v[64:67], v[144:147], 0
	v_mfma_f32_16x16x32_bf16 v[140:143], v[56:59], v[168:171], 0
	v_mfma_f32_16x16x32_bf16 v[136:139], v[64:67], v[168:171], 0
	v_mfma_f32_16x16x32_bf16 v[124:127], v[56:59], v[176:179], 0
	v_mfma_f32_16x16x32_bf16 v[120:123], v[64:67], v[176:179], 0
	v_mfma_f32_16x16x32_bf16 v[108:111], v[56:59], v[200:203], 0
	v_mfma_f32_16x16x32_bf16 v[104:107], v[64:67], v[200:203], 0
	v_mfma_f32_16x16x32_bf16 v[164:167], v[60:63], v[156:159], v[164:167]
	v_mfma_f32_16x16x32_bf16 v[160:163], v[68:71], v[156:159], v[160:163]
	v_mfma_f32_16x16x32_bf16 v[140:143], v[60:63], v[172:175], v[140:143]
	v_mfma_f32_16x16x32_bf16 v[136:139], v[68:71], v[172:175], v[136:139]
	v_mfma_f32_16x16x32_bf16 v[124:127], v[60:63], v[180:183], v[124:127]
	v_mfma_f32_16x16x32_bf16 v[120:123], v[68:71], v[180:183], v[120:123]
	v_mfma_f32_16x16x32_bf16 v[108:111], v[60:63], v[204:207], v[108:111]
	v_mfma_f32_16x16x32_bf16 v[104:107], v[68:71], v[204:207], v[104:107]
	s_setprio 0
	s_setprio 1
	v_mfma_f32_16x16x32_bf16 v[152:155], v[72:75], v[144:147], 0
	v_mfma_f32_16x16x32_bf16 v[132:135], v[72:75], v[168:171], 0
	v_mfma_f32_16x16x32_bf16 v[128:131], v[80:83], v[168:171], 0
	v_mfma_f32_16x16x32_bf16 v[116:119], v[72:75], v[176:179], 0
	v_mfma_f32_16x16x32_bf16 v[112:115], v[80:83], v[176:179], 0
	v_mfma_f32_16x16x32_bf16 v[100:103], v[72:75], v[200:203], 0
	v_mfma_f32_16x16x32_bf16 v[96:99], v[80:83], v[200:203], 0
	v_mfma_f32_16x16x32_bf16 v[152:155], v[76:79], v[156:159], v[152:155]
	v_mfma_f32_16x16x32_bf16 v[144:147], v[80:83], v[144:147], 0
	v_mfma_f32_16x16x32_bf16 v[132:135], v[76:79], v[172:175], v[132:135]
	v_mfma_f32_16x16x32_bf16 v[128:131], v[84:87], v[172:175], v[128:131]
	v_mfma_f32_16x16x32_bf16 v[116:119], v[76:79], v[180:183], v[116:119]
	v_mfma_f32_16x16x32_bf16 v[112:115], v[84:87], v[180:183], v[112:115]
	v_mfma_f32_16x16x32_bf16 v[100:103], v[76:79], v[204:207], v[100:103]
	v_mfma_f32_16x16x32_bf16 v[96:99], v[84:87], v[204:207], v[96:99]
	v_mfma_f32_16x16x32_bf16 v[144:147], v[84:87], v[156:159], v[144:147]
	s_setprio 0
	s_barrier
	s_add_i32 s81, s74, s59
	v_lshl_add_u64 v[208:209], s[54:55], 0, v[186:187]
	s_mov_b32 m0, s81
	ds_read_b128 v[148:151], v219 offset:16384
	ds_read_b128 v[156:159], v219 offset:17408
	ds_read_b128 v[168:171], v219 offset:18432
	ds_read_b128 v[172:175], v219 offset:19456
	ds_read_b128 v[176:179], v219 offset:20480
	ds_read_b128 v[180:183], v219 offset:21504
	ds_read_b128 v[200:203], v219 offset:22528
	ds_read_b128 v[204:207], v219 offset:23552
	global_load_lds_dwordx4 v[208:209], off
	s_add_i32 m0, s81, 0x2000
	s_add_u32 s82, s54, 0x40000
	v_lshl_add_u64 v[210:211], s[54:55], 0, v[190:191]
	s_addc_u32 s83, s55, 0
	s_add_i32 s81, s75, s59
	global_load_lds_dwordx4 v[210:211], off
	v_lshl_add_u64 v[222:223], s[82:83], 0, v[186:187]
	s_mov_b32 m0, s81
	v_lshl_add_u64 v[224:225], s[56:57], 0, v[188:189]
	global_load_lds_dwordx4 v[222:223], off
	v_lshl_add_u64 v[222:223], s[82:83], 0, v[190:191]
	s_add_i32 m0, s81, 0x2000
	s_nop 0
	global_load_lds_dwordx4 v[222:223], off
	v_lshl_add_u64 v[222:223], s[56:57], 0, v[184:185]
	s_mov_b32 m0, s64
	s_nop 0
	global_load_lds_dwordx4 v[222:223], off
	s_mov_b32 m0, s65
	s_nop 0
	global_load_lds_dwordx4 v[224:225], off
	s_waitcnt vmcnt(8)
	s_waitcnt lgkmcnt(0)
	s_barrier
	s_setprio 1
	s_waitcnt lgkmcnt(0)
	v_mfma_f32_16x16x32_bf16 v[92:95], v[56:59], v[148:151], 0
	v_mfma_f32_16x16x32_bf16 v[88:91], v[64:67], v[148:151], 0
	v_mfma_f32_16x16x32_bf16 v[44:47], v[56:59], v[168:171], 0
	v_mfma_f32_16x16x32_bf16 v[40:43], v[64:67], v[168:171], 0
	v_mfma_f32_16x16x32_bf16 v[28:31], v[56:59], v[176:179], 0
	v_mfma_f32_16x16x32_bf16 v[24:27], v[64:67], v[176:179], 0
	v_mfma_f32_16x16x32_bf16 v[12:15], v[56:59], v[200:203], 0
	v_mfma_f32_16x16x32_bf16 v[8:11], v[64:67], v[200:203], 0
	v_mfma_f32_16x16x32_bf16 v[92:95], v[60:63], v[156:159], v[92:95]
	v_mfma_f32_16x16x32_bf16 v[88:91], v[68:71], v[156:159], v[88:91]
	v_mfma_f32_16x16x32_bf16 v[44:47], v[60:63], v[172:175], v[44:47]
	v_mfma_f32_16x16x32_bf16 v[40:43], v[68:71], v[172:175], v[40:43]
	v_mfma_f32_16x16x32_bf16 v[28:31], v[60:63], v[180:183], v[28:31]
	v_mfma_f32_16x16x32_bf16 v[24:27], v[68:71], v[180:183], v[24:27]
	v_mfma_f32_16x16x32_bf16 v[12:15], v[60:63], v[204:207], v[12:15]
	v_mfma_f32_16x16x32_bf16 v[8:11], v[68:71], v[204:207], v[8:11]
	s_setprio 0
	s_setprio 1
	v_mfma_f32_16x16x32_bf16 v[52:55], v[72:75], v[148:151], 0
	v_mfma_f32_16x16x32_bf16 v[48:51], v[80:83], v[148:151], 0
	v_mfma_f32_16x16x32_bf16 v[36:39], v[72:75], v[168:171], 0
	v_mfma_f32_16x16x32_bf16 v[32:35], v[80:83], v[168:171], 0
	v_mfma_f32_16x16x32_bf16 v[20:23], v[72:75], v[176:179], 0
	v_mfma_f32_16x16x32_bf16 v[16:19], v[80:83], v[176:179], 0
	v_mfma_f32_16x16x32_bf16 v[4:7], v[72:75], v[200:203], 0
	v_mfma_f32_16x16x32_bf16 v[0:3], v[80:83], v[200:203], 0
	v_mfma_f32_16x16x32_bf16 v[52:55], v[76:79], v[156:159], v[52:55]
	v_mfma_f32_16x16x32_bf16 v[48:51], v[84:87], v[156:159], v[48:51]
	v_mfma_f32_16x16x32_bf16 v[36:39], v[76:79], v[172:175], v[36:39]
	v_mfma_f32_16x16x32_bf16 v[32:35], v[84:87], v[172:175], v[32:35]
	v_mfma_f32_16x16x32_bf16 v[20:23], v[76:79], v[180:183], v[20:23]
	v_mfma_f32_16x16x32_bf16 v[16:19], v[84:87], v[180:183], v[16:19]
	v_mfma_f32_16x16x32_bf16 v[4:7], v[76:79], v[204:207], v[4:7]
	v_mfma_f32_16x16x32_bf16 v[0:3], v[84:87], v[204:207], v[0:3]
	s_setprio 0
	s_barrier
	s_add_i32 s81, 0, 0x18000
	s_add_i32 s82, 0, 0x1c000
	v_add_u32_e32 v68, s81, v215
	v_add_u32_e32 v84, s82, v215
	ds_read_b128 v[56:59], v68
	ds_read_b128 v[60:63], v68 offset:1024
	ds_read_b128 v[64:67], v68 offset:2048
	ds_read_b128 v[68:71], v68 offset:3072
	ds_read_b128 v[72:75], v84
	ds_read_b128 v[76:79], v84 offset:1024
	ds_read_b128 v[80:83], v84 offset:2048
	ds_read_b128 v[84:87], v84 offset:3072
	s_add_u32 s56, s56, 0x40000
	s_addc_u32 s57, s57, 0
	s_mov_b32 m0, s66
	v_lshl_add_u64 v[226:227], s[56:57], 0, v[184:185]
	ds_read_b128 v[148:151], v219 offset:32768
	ds_read_b128 v[156:159], v219 offset:33792
	ds_read_b128 v[168:171], v219 offset:34816
	ds_read_b128 v[172:175], v219 offset:35840
	ds_read_b128 v[176:179], v219 offset:36864
	ds_read_b128 v[180:183], v219 offset:37888
	ds_read_b128 v[200:203], v219 offset:38912
	ds_read_b128 v[204:207], v219 offset:39936
	global_load_lds_dwordx4 v[226:227], off
	v_lshl_add_u64 v[226:227], s[56:57], 0, v[188:189]
	s_mov_b32 m0, s67
	s_nop 0
	global_load_lds_dwordx4 v[226:227], off
	s_waitcnt vmcnt(8)
	s_waitcnt lgkmcnt(0)
	s_barrier
	s_setprio 1
	s_waitcnt lgkmcnt(0)
	v_mfma_f32_16x16x32_bf16 v[164:167], v[56:59], v[148:151], v[164:167]
	v_mfma_f32_16x16x32_bf16 v[160:163], v[64:67], v[148:151], v[160:163]
	v_mfma_f32_16x16x32_bf16 v[140:143], v[56:59], v[168:171], v[140:143]
	v_mfma_f32_16x16x32_bf16 v[136:139], v[64:67], v[168:171], v[136:139]
	v_mfma_f32_16x16x32_bf16 v[124:127], v[56:59], v[176:179], v[124:127]
	v_mfma_f32_16x16x32_bf16 v[120:123], v[64:67], v[176:179], v[120:123]
	v_mfma_f32_16x16x32_bf16 v[108:111], v[56:59], v[200:203], v[108:111]
	v_mfma_f32_16x16x32_bf16 v[104:107], v[64:67], v[200:203], v[104:107]
	v_mfma_f32_16x16x32_bf16 v[164:167], v[60:63], v[156:159], v[164:167]
	v_mfma_f32_16x16x32_bf16 v[160:163], v[68:71], v[156:159], v[160:163]
	v_mfma_f32_16x16x32_bf16 v[140:143], v[60:63], v[172:175], v[140:143]
	v_mfma_f32_16x16x32_bf16 v[136:139], v[68:71], v[172:175], v[136:139]
	v_mfma_f32_16x16x32_bf16 v[124:127], v[60:63], v[180:183], v[124:127]
	v_mfma_f32_16x16x32_bf16 v[120:123], v[68:71], v[180:183], v[120:123]
	v_mfma_f32_16x16x32_bf16 v[108:111], v[60:63], v[204:207], v[108:111]
	v_mfma_f32_16x16x32_bf16 v[104:107], v[68:71], v[204:207], v[104:107]
	s_setprio 0
	s_setprio 1
	v_mfma_f32_16x16x32_bf16 v[152:155], v[72:75], v[148:151], v[152:155]
	v_mfma_f32_16x16x32_bf16 v[144:147], v[80:83], v[148:151], v[144:147]
	v_mfma_f32_16x16x32_bf16 v[132:135], v[72:75], v[168:171], v[132:135]
	v_mfma_f32_16x16x32_bf16 v[128:131], v[80:83], v[168:171], v[128:131]
	v_mfma_f32_16x16x32_bf16 v[116:119], v[72:75], v[176:179], v[116:119]
	v_mfma_f32_16x16x32_bf16 v[112:115], v[80:83], v[176:179], v[112:115]
	v_mfma_f32_16x16x32_bf16 v[100:103], v[72:75], v[200:203], v[100:103]
	v_mfma_f32_16x16x32_bf16 v[96:99], v[80:83], v[200:203], v[96:99]
	v_mfma_f32_16x16x32_bf16 v[152:155], v[76:79], v[156:159], v[152:155]
	v_mfma_f32_16x16x32_bf16 v[148:151], v[84:87], v[156:159], v[144:147]
	v_mfma_f32_16x16x32_bf16 v[132:135], v[76:79], v[172:175], v[132:135]
	v_mfma_f32_16x16x32_bf16 v[128:131], v[84:87], v[172:175], v[128:131]
	v_mfma_f32_16x16x32_bf16 v[116:119], v[76:79], v[180:183], v[116:119]
	v_mfma_f32_16x16x32_bf16 v[112:115], v[84:87], v[180:183], v[112:115]
	v_mfma_f32_16x16x32_bf16 v[100:103], v[76:79], v[204:207], v[100:103]
	v_mfma_f32_16x16x32_bf16 v[96:99], v[84:87], v[204:207], v[96:99]
	s_setprio 0
	s_barrier
	s_add_i32 s56, s81, s59
	v_lshl_add_u64 v[208:209], v[208:209], 0, s[36:37]
	s_mov_b32 m0, s56
	ds_read_b128 v[144:147], v219 offset:49152
	ds_read_b128 v[156:159], v219 offset:50176
	ds_read_b128 v[168:171], v219 offset:51200
	ds_read_b128 v[172:175], v219 offset:52224
	ds_read_b128 v[176:179], v219 offset:53248
	ds_read_b128 v[180:183], v219 offset:54272
	ds_read_b128 v[200:203], v219 offset:55296
	ds_read_b128 v[204:207], v219 offset:56320
	global_load_lds_dwordx4 v[208:209], off
	s_add_i32 m0, s56, 0x2000
	s_add_u32 s54, s54, 0x40080
	v_lshl_add_u64 v[208:209], v[210:211], 0, s[36:37]
	s_addc_u32 s55, s55, 0
	s_add_i32 s56, s82, s59
	global_load_lds_dwordx4 v[208:209], off
	v_lshl_add_u64 v[208:209], s[54:55], 0, v[186:187]
	s_mov_b32 m0, s56
	s_nop 0
	global_load_lds_dwordx4 v[208:209], off
	v_lshl_add_u64 v[208:209], s[54:55], 0, v[190:191]
	s_add_i32 m0, s56, 0x2000
	s_nop 0
	global_load_lds_dwordx4 v[208:209], off
	v_lshl_add_u64 v[208:209], v[222:223], 0, s[36:37]
	s_mov_b32 m0, s69
	s_nop 0
	global_load_lds_dwordx4 v[208:209], off
	v_lshl_add_u64 v[208:209], v[224:225], 0, s[36:37]
	s_mov_b32 m0, s70
	s_nop 0
	global_load_lds_dwordx4 v[208:209], off
	s_waitcnt vmcnt(8)
	s_waitcnt lgkmcnt(0)
	s_barrier
	s_setprio 1
	s_waitcnt lgkmcnt(0)
	v_mfma_f32_16x16x32_bf16 v[92:95], v[56:59], v[144:147], v[92:95]
	v_mfma_f32_16x16x32_bf16 v[88:91], v[64:67], v[144:147], v[88:91]
	v_mfma_f32_16x16x32_bf16 v[44:47], v[56:59], v[168:171], v[44:47]
	v_mfma_f32_16x16x32_bf16 v[40:43], v[64:67], v[168:171], v[40:43]
	v_mfma_f32_16x16x32_bf16 v[28:31], v[56:59], v[176:179], v[28:31]
	v_mfma_f32_16x16x32_bf16 v[24:27], v[64:67], v[176:179], v[24:27]
	v_mfma_f32_16x16x32_bf16 v[12:15], v[56:59], v[200:203], v[12:15]
	v_mfma_f32_16x16x32_bf16 v[8:11], v[64:67], v[200:203], v[8:11]
	v_mfma_f32_16x16x32_bf16 v[92:95], v[60:63], v[156:159], v[92:95]
	v_mfma_f32_16x16x32_bf16 v[88:91], v[68:71], v[156:159], v[88:91]
	v_mfma_f32_16x16x32_bf16 v[44:47], v[60:63], v[172:175], v[44:47]
	v_mfma_f32_16x16x32_bf16 v[40:43], v[68:71], v[172:175], v[40:43]
	v_mfma_f32_16x16x32_bf16 v[28:31], v[60:63], v[180:183], v[28:31]
	v_mfma_f32_16x16x32_bf16 v[24:27], v[68:71], v[180:183], v[24:27]
	v_mfma_f32_16x16x32_bf16 v[12:15], v[60:63], v[204:207], v[12:15]
	v_mfma_f32_16x16x32_bf16 v[8:11], v[68:71], v[204:207], v[8:11]
	s_setprio 0
	s_setprio 1
	v_mfma_f32_16x16x32_bf16 v[52:55], v[72:75], v[144:147], v[52:55]
	v_mfma_f32_16x16x32_bf16 v[48:51], v[80:83], v[144:147], v[48:51]
	v_mfma_f32_16x16x32_bf16 v[36:39], v[72:75], v[168:171], v[36:39]
	v_mfma_f32_16x16x32_bf16 v[32:35], v[80:83], v[168:171], v[32:35]
	v_mfma_f32_16x16x32_bf16 v[20:23], v[72:75], v[176:179], v[20:23]
	v_mfma_f32_16x16x32_bf16 v[16:19], v[80:83], v[176:179], v[16:19]
	v_mfma_f32_16x16x32_bf16 v[4:7], v[72:75], v[200:203], v[4:7]
	v_mfma_f32_16x16x32_bf16 v[0:3], v[80:83], v[200:203], v[0:3]
	v_mfma_f32_16x16x32_bf16 v[52:55], v[76:79], v[156:159], v[52:55]
	v_mfma_f32_16x16x32_bf16 v[48:51], v[84:87], v[156:159], v[48:51]
	v_mfma_f32_16x16x32_bf16 v[36:39], v[76:79], v[172:175], v[36:39]
	v_mfma_f32_16x16x32_bf16 v[32:35], v[84:87], v[172:175], v[32:35]
	v_mfma_f32_16x16x32_bf16 v[20:23], v[76:79], v[180:183], v[20:23]
	v_mfma_f32_16x16x32_bf16 v[16:19], v[84:87], v[180:183], v[16:19]
	v_mfma_f32_16x16x32_bf16 v[4:7], v[76:79], v[204:207], v[4:7]
	v_mfma_f32_16x16x32_bf16 v[0:3], v[84:87], v[204:207], v[0:3]
	s_setprio 0
	s_barrier
	s_add_i32 s80, s80, 2
	s_add_u32 s52, s52, 0x100
	s_addc_u32 s53, s53, 0
	s_add_u32 s78, s78, 0x100
	s_addc_u32 s79, s79, 0
	s_cmp_gt_u32 s80, 13
